# hg_state unit loop: entry path drains, loop-head waits recounted for 18 loads + 8 stores (on top of the hg_out wait placement)
# speedup vs baseline: 1.0071x; 1.0024x over previous
; DI void hg_state_units(LAS unsigned char* L, int u0, int G, const float* LOGF, const bf16* IHG, bf16* ST, float* DEC, int tid, int wave, int lane) {
;     ...
;     int unit = u0; if (unit >= 2048) return;
;     float g[16]; bf16x8 v8[2];
;     ...
;     HGS_LOAD(unit);
.LBB0_157:
	s_or_b64 exec, exec, s[0:1]
	s_xor_b64 s[0:1], s[44:45], -1
	v_writelane_b32 v255, s0, 5
	s_waitcnt lgkmcnt(0)
	s_barrier
	v_writelane_b32 v255, s1, 6
	s_mov_b32 s0, -1
	v_readlane_b32 s6, v253, 18
	v_mbcnt_lo_u32_b32 v0, s0, 0
	v_mbcnt_hi_u32_b32 v0, s0, v0
	v_readlane_b32 s7, v253, 19
	v_add_u32_e32 v12, s68, v0
	s_mov_b64 s[0:1], 0
	v_cndmask_b32_e64 v0, 0, 1, s[6:7]
	v_cmp_ne_u32_e64 s[4:5], 1, v0
	s_andn2_b64 vcc, exec, s[6:7]
	v_readfirstlane_b32 s6, v12
	s_cbranch_vccnz .LBB0_164
	v_readlane_b32 s8, v252, 0
	v_mov_b64_e32 v[0:1], s[0:1]
	v_readlane_b32 s9, v252, 1
	v_readlane_b32 s10, v252, 2
	v_readlane_b32 s11, v252, 3
	s_mov_b64 s[8:9], 0x17000000
	v_ashrrev_i32_e32 v42, 7, v12
	v_lshl_add_u64 v[0:1], s[10:11], 0, v[0:1]
	v_lshl_add_u64 v[24:25], v[0:1], 0, s[8:9]
	s_mov_b64 s[8:9], 0x1b000000
	v_lshl_add_u64 v[26:27], v[0:1], 0, s[8:9]
	v_lshlrev_b32_e32 v32, 4, v42
	v_readlane_b32 s8, v253, 21
	v_readlane_b32 s7, v253, 24
	v_and_b32_e32 v43, 0x7f, v12
	v_ashrrev_i32_e32 v33, 31, v32
	v_readlane_b32 s9, v253, 22
	s_lshl_b32 s36, s7, 2
	v_lshl_add_u64 v[2:3], v[26:27], 0, s[36:37]
	v_lshl_add_u64 v[0:1], s[8:9], 0, v[32:33]
	v_lshlrev_b32_e32 v160, 2, v43
	v_lshl_add_u64 v[2:3], v[2:3], 0, v[160:161]
	v_lshlrev_b64 v[0:1], 12, v[0:1]
	v_lshl_add_u64 v[0:1], v[2:3], 0, v[0:1]
	v_add_co_u32_e32 v2, vcc, s40, v0
	s_movk_i32 s24, 0x4000
	s_nop 0
	v_addc_co_u32_e32 v3, vcc, 0, v1, vcc
	v_add_co_u32_e32 v20, vcc, s24, v0
	s_movk_i32 s25, 0x6000
	s_nop 0
	v_addc_co_u32_e32 v21, vcc, 0, v1, vcc
	v_add_co_u32_e32 v6, vcc, s25, v0
	s_mov_b32 s26, 0x8000
	s_nop 0
	v_addc_co_u32_e32 v7, vcc, 0, v1, vcc
	v_add_co_u32_e32 v8, vcc, s26, v0
	s_mov_b32 s27, 0xa000
	s_nop 0
	v_addc_co_u32_e32 v9, vcc, 0, v1, vcc
	v_add_co_u32_e32 v10, vcc, s27, v0
	s_mov_b32 s28, 0xc000
	s_nop 0
	v_addc_co_u32_e32 v11, vcc, 0, v1, vcc
	v_add_co_u32_e32 v28, vcc, s28, v0
	s_mov_b32 s10, 0xe000
	s_nop 0
	v_addc_co_u32_e32 v29, vcc, 0, v1, vcc
	s_lshl_b32 s36, s7, 1
	v_lshlrev_b32_e32 v18, 4, v12
	v_ashrrev_i32_e32 v34, 4, v12
	v_add_co_u32_e32 v30, vcc, s10, v0
	v_lshl_add_u64 v[16:17], v[24:25], 0, s[36:37]
	v_and_b32_e32 v38, 0xf0, v18
	v_mov_b32_e32 v39, v161
	v_ashrrev_i32_e32 v35, 31, v34
	v_addc_co_u32_e32 v31, vcc, 0, v1, vcc
	s_mov_b32 s35, 0xf000
	v_lshl_add_u64 v[22:23], v[16:17], 0, v[38:39]
	v_lshl_add_u64 v[16:17], s[8:9], 0, v[34:35]
	v_add_co_u32_e32 v14, vcc, s35, v0
	v_lshlrev_b64 v[16:17], 11, v[16:17]
	s_nop 0
	v_addc_co_u32_e32 v15, vcc, 0, v1, vcc
	v_lshl_add_u64 v[16:17], v[22:23], 0, v[16:17]
	global_load_dword v4, v[20:21], off
	global_load_dword v5, v[6:7], off offset:-4096
	s_nop 0
	global_load_dword v6, v[6:7], off
	s_nop 0
	global_load_dword v7, v[8:9], off offset:-4096
	s_nop 0
	global_load_dword v8, v[8:9], off
	s_nop 0
	global_load_dword v9, v[10:11], off offset:-4096
	s_nop 0
	global_load_dword v10, v[10:11], off
	s_nop 0
	global_load_dword v11, v[28:29], off offset:-4096
	s_nop 0
	global_load_dword v0, v[0:1], off
	s_nop 0
	global_load_dword v15, v[14:15], off
	s_nop 0
	global_load_dwordx4 v[16:19], v[16:17], off
	v_add_u32_e32 v1, 0x200, v12
	v_ashrrev_i32_e32 v36, 4, v1
	v_ashrrev_i32_e32 v37, 31, v36
	s_ashr_i32 s6, s6, 6
	v_lshl_add_u64 v[40:41], s[8:9], 0, v[36:37]
	v_and_b32_e32 v45, 15, v12
	v_lshlrev_b64 v[40:41], 11, v[40:41]
	v_add_u32_e32 v14, 0, v38
	v_lshl_add_u64 v[38:39], v[24:25], 0, v[38:39]
	v_lshl_or_b32 v24, s6, 4, v45
	v_lshl_add_u64 v[22:23], v[22:23], 0, v[40:41]
	v_lshrrev_b32_e32 v40, 1, v12
	v_ashrrev_i32_e32 v25, 31, v24
	v_and_b32_e32 v40, 24, v40
	v_bfe_u32 v41, v12, 2, 2
	v_lshlrev_b64 v[24:25], 8, v[24:25]
	v_or_b32_e32 v50, v40, v41
	v_lshl_add_u64 v[24:25], s[0:1], 0, v[24:25]
	v_mov_b32_e32 v41, v161
	v_lshlrev_b32_e32 v44, 3, v12
	v_lshl_add_u64 v[24:25], v[24:25], 0, v[40:41]
	v_add_u32_e32 v46, 0, v160
	v_mul_u32_u24_e32 v40, 0x8c, v43
	v_lshlrev_b32_e32 v41, 5, v42
	s_lshl_b32 s6, s6, 5
	s_movk_i32 s14, 0x140
	v_add3_u32 v47, v46, v40, v41
	s_add_i32 s6, s6, 0
	v_and_b32_e32 v40, 24, v44
	v_mul_lo_u32 v41, v34, s14
	v_and_b32_e32 v13, 63, v12
	v_add_u32_e32 v40, s6, v40
	v_cmp_lt_i32_e64 s[6:7], 0, v42
	v_cmp_lt_i32_e64 s[8:9], 1, v42
	v_cmp_lt_i32_e64 s[10:11], 2, v42
	v_cmp_lt_i32_e64 s[12:13], 3, v42
	v_mul_lo_u32 v42, v36, s14
	v_add_u32_e32 v48, v14, v41
	v_mul_u32_u24_e32 v41, 0x140, v50
	v_add_u32_e32 v49, v14, v42
	v_and_b32_e32 v14, 48, v12
	v_add_u32_e32 v50, v40, v41
	v_or_b32_e32 v40, 48, v13
	v_or_b32_e32 v13, 0x70, v13
	v_add_u32_e32 v14, 0, v14
	v_mul_u32_u24_e32 v13, 0x90, v13
	v_add_u32_e32 v53, v14, v13
	s_movk_i32 s14, 0x80
	v_mov_b32_e32 v13, v161
	v_lshl_add_u32 v54, v12, 2, 0
	v_cmp_gt_u32_e64 s[14:15], s14, v12
	v_lshl_add_u64 v[12:13], v[12:13], 2, s[0:1]
	v_readlane_b32 s0, v254, 20
	global_load_dword v1, v[2:3], off offset:-4096
	s_nop 0
	global_load_dword v2, v[2:3], off
	s_nop 0
	global_load_dword v3, v[20:21], off offset:-4096
	s_nop 0
	global_load_dwordx4 v[20:23], v[22:23], off
	v_mul_u32_u24_e32 v42, 0x90, v45
	v_mul_u32_u24_e32 v40, 0x90, v40
	v_readlane_b32 s1, v254, 21
	v_add_u32_e32 v51, v14, v42
	v_add_u32_e32 v52, v14, v40
	v_lshl_add_u64 v[42:43], s[0:1], 0, v[12:13]
	global_load_dword v12, v[28:29], off
	global_load_dword v13, v[30:31], off offset:-4096
	global_load_dword v14, v[30:31], off
	v_readlane_b32 s0, v254, 32
	v_readlane_b32 s1, v254, 33
	v_readlane_b32 s22, v254, 25
	v_lshl_add_u64 v[40:41], v[26:27], 0, v[160:161]
	v_lshl_add_u64 v[44:45], s[0:1], 0, v[24:25]
	v_readlane_b32 s0, v254, 36
	v_readlane_b32 s18, v254, 23
	v_readlane_b32 s19, v254, 22
	s_mov_b32 s20, s0
	v_readlane_b32 s23, v254, 26
	v_readlane_b32 s1, v254, 37
	s_waitcnt vmcnt(0)
	s_branch .LBB0_160

; #define LAS __attribute__((address_space(3)))
; DI unsigned pk2(float lo, float hi) { f32x2_t v = {lo, hi}; bf16x2_t b = __builtin_convertvector(v, bf16x2_t); return __builtin_bit_cast(unsigned, b); }
; DI float fexp(float x) { return __builtin_amdgcn_exp2f(x * LOG2E); }
; DI void hg_state_units(LAS unsigned char* L, int u0, int G, const float* LOGF, const bf16* IHG, bf16* ST, float* DEC, int tid, int wave, int lane) {
;     ...
;     for (;;) {
;         float tot = 0.f;
; #pragma unroll
;         for (int i = 0; i < 16; ++i) tot += g[i];
;         segtot[seg * 128 + c] = tot;
; #pragma unroll
;         for (int i = 0; i < 2; ++i) { const int cid = tid + 512 * i, kv = cid >> 4, dvs = (cid & 15) * 8; *(LAS bf16x8*)(Vs + kv * 160 + dvs) = v8[i]; }
;         __syncthreads();
;         float off = 0.f, total = 0.f;
; #pragma unroll
;         for (int s = 0; s < 4; ++s) { const float t_ = segtot[s * 128 + c]; if (s < seg) off += t_; total += t_; }
;         float run = off; float kh[16];
; #pragma unroll
;         for (int i = 0; i < 16; ++i) { run += g[i]; kh[i] = (1.f - fexp(g[i])) * fexp(total - run); }
;         { u32x4 w0, w1; w0.x = pk2(kh[0], kh[1]); w0.y = pk2(kh[2], kh[3]); w0.z = pk2(kh[4], kh[5]); w0.w = pk2(kh[6], kh[7]);
;           w1.x = pk2(kh[8], kh[9]); w1.y = pk2(kh[10], kh[11]); w1.z = pk2(kh[12], kh[13]); w1.w = pk2(kh[14], kh[15]);
;           *(LAS u32x4*)(KhT + c * 72 + 16 * seg) = w0; *(LAS u32x4*)(KhT + c * 72 + 16 * seg + 8) = w1; }
;         if (seg == 0) DEC[(size_t)unit * 128 + c] = fexp(total);
.LBB0_160:
	s_waitcnt vmcnt(25)
	v_add_f32_e32 v24, 0, v0
	s_waitcnt vmcnt(24)
	v_add_f32_e32 v24, v1, v24
	s_waitcnt vmcnt(23)
	v_add_f32_e32 v24, v2, v24
	s_waitcnt vmcnt(14)
	v_add_f32_e32 v24, v3, v24
	v_add_f32_e32 v24, v4, v24
	v_add_f32_e32 v24, v5, v24
	v_add_f32_e32 v24, v6, v24
	v_add_f32_e32 v24, v7, v24
	v_add_f32_e32 v24, v8, v24
	v_add_f32_e32 v24, v9, v24
	v_add_f32_e32 v24, v10, v24
	v_add_f32_e32 v24, v11, v24
	s_waitcnt vmcnt(13)
	v_add_f32_e32 v24, v12, v24
	s_waitcnt vmcnt(12)
	v_add_f32_e32 v24, v13, v24
	s_waitcnt vmcnt(10)
	v_add_f32_e32 v24, v14, v24
	v_add_f32_e32 v24, v15, v24
	ds_write_b32 v54, v24 offset:38912
	v_mul_f32_e32 v24, 0x3fb8aa3b, v0
	v_exp_f32_e32 v26, v24
	v_mul_f32_e32 v24, 0x3fb8aa3b, v1
	v_exp_f32_e32 v27, v24
	s_waitcnt vmcnt(8)
	ds_write_b128 v48, v[16:19] offset:18432
	ds_write_b128 v49, v[20:23] offset:18432
	s_waitcnt lgkmcnt(0)
	s_barrier
	ds_read2st64_b32 v[24:25], v46 offset0:152 offset1:154
	v_pk_add_f32 v[26:27], v[26:27], 1.0 op_sel_hi:[1,0] neg_lo:[1,0] neg_hi:[1,0]
	s_waitcnt lgkmcnt(0)
	v_add_f32_e32 v30, 0, v24
	v_cndmask_b32_e64 v24, 0, v30, s[6:7]
	v_add_f32_e32 v28, v25, v24
	v_cndmask_b32_e64 v24, v24, v28, s[8:9]
	ds_read2st64_b32 v[28:29], v46 offset0:156 offset1:158
	s_waitcnt lgkmcnt(0)
	v_add_f32_e32 v31, v28, v24
	v_cndmask_b32_e64 v24, v24, v31, s[10:11]
	v_add_f32_e32 v31, v29, v24
	v_cndmask_b32_e64 v24, v24, v31, s[12:13]
	v_add_f32_e32 v55, v0, v24
	v_add_f32_e32 v60, v1, v55
	v_add_f32_e32 v61, v2, v60
	v_add_f32_e32 v62, v3, v61
	v_add_f32_e32 v63, v4, v62
	v_add_f32_e32 v64, v5, v63
	v_add_f32_e32 v65, v6, v64
	v_add_f32_e32 v66, v7, v65
	v_add_f32_e32 v67, v8, v66
	v_add_f32_e32 v68, v9, v67
	v_add_f32_e32 v69, v10, v68
	v_add_f32_e32 v70, v11, v69
	v_add_f32_e32 v31, v12, v70
	v_mov_b32_e32 v24, v25
	v_mov_b32_e32 v25, v13
	v_pk_add_f32 v[56:57], v[30:31], v[24:25]
	v_mov_b32_e32 v24, v28
	v_mov_b32_e32 v25, v14
	v_pk_add_f32 v[58:59], v[56:57], v[24:25]
	v_mov_b32_e32 v24, v29
	v_mov_b32_e32 v25, v15
	v_pk_add_f32 v[24:25], v[58:59], v[24:25]
	s_nop 0
	v_sub_f32_e32 v28, v24, v55
	v_sub_f32_e32 v29, v24, v60
	v_mul_f32_e32 v28, 0x3fb8aa3b, v28
	v_mul_f32_e32 v29, 0x3fb8aa3b, v29
	v_exp_f32_e32 v28, v28
	v_exp_f32_e32 v29, v29
	v_sub_f32_e32 v30, v24, v61
	v_sub_f32_e32 v55, v24, v62
	v_mul_f32_e32 v30, 0x3fb8aa3b, v30
	v_pk_mul_f32 v[26:27], v[26:27], v[28:29]
	v_mul_f32_e32 v28, 0x3fb8aa3b, v2
	v_mul_f32_e32 v29, 0x3fb8aa3b, v3
	v_exp_f32_e32 v28, v28
	v_exp_f32_e32 v29, v29
	v_mul_f32_e32 v55, 0x3fb8aa3b, v55
	v_exp_f32_e32 v60, v30
	v_exp_f32_e32 v61, v55
	v_pk_add_f32 v[28:29], v[28:29], 1.0 op_sel_hi:[1,0] neg_lo:[1,0] neg_hi:[1,0]
	v_mul_f32_e32 v30, 0x3fb8aa3b, v4
	v_sub_f32_e32 v55, v24, v64
	v_pk_mul_f32 v[28:29], v[28:29], v[60:61]
	v_exp_f32_e32 v60, v30
	v_mul_f32_e32 v30, 0x3fb8aa3b, v5
	v_exp_f32_e32 v61, v30
	v_sub_f32_e32 v30, v24, v63
	v_mul_f32_e32 v30, 0x3fb8aa3b, v30
	v_mul_f32_e32 v55, 0x3fb8aa3b, v55
	v_exp_f32_e32 v62, v30
	v_exp_f32_e32 v63, v55
	v_pk_add_f32 v[60:61], v[60:61], 1.0 op_sel_hi:[1,0] neg_lo:[1,0] neg_hi:[1,0]
	v_mul_f32_e32 v30, 0x3fb8aa3b, v6
	v_sub_f32_e32 v55, v24, v66
	v_pk_mul_f32 v[60:61], v[60:61], v[62:63]
	v_exp_f32_e32 v62, v30
	v_mul_f32_e32 v30, 0x3fb8aa3b, v7
	v_exp_f32_e32 v63, v30
	v_sub_f32_e32 v30, v24, v65
	v_mul_f32_e32 v30, 0x3fb8aa3b, v30
	v_mul_f32_e32 v55, 0x3fb8aa3b, v55
	v_exp_f32_e32 v64, v30
	v_exp_f32_e32 v65, v55
	v_pk_add_f32 v[62:63], v[62:63], 1.0 op_sel_hi:[1,0] neg_lo:[1,0] neg_hi:[1,0]
	v_cvt_pk_bf16_f32 v26, v26, v27
	v_cvt_pk_bf16_f32 v27, v28, v29
	v_pk_mul_f32 v[62:63], v[62:63], v[64:65]
	v_cvt_pk_bf16_f32 v28, v60, v61
	v_cvt_pk_bf16_f32 v29, v62, v63
	ds_write_b128 v47, v[26:29]
	v_mul_f32_e32 v26, 0x3fb8aa3b, v8
	v_mul_f32_e32 v27, 0x3fb8aa3b, v9
	v_sub_f32_e32 v28, v24, v67
	v_sub_f32_e32 v29, v24, v68
	v_exp_f32_e32 v26, v26
	v_exp_f32_e32 v27, v27
	v_mul_f32_e32 v28, 0x3fb8aa3b, v28
	v_mul_f32_e32 v29, 0x3fb8aa3b, v29
	v_exp_f32_e32 v28, v28
	v_exp_f32_e32 v29, v29
	v_pk_add_f32 v[26:27], v[26:27], 1.0 op_sel_hi:[1,0] neg_lo:[1,0] neg_hi:[1,0]
	v_sub_f32_e32 v30, v24, v69
	v_sub_f32_e32 v55, v24, v70
	v_pk_mul_f32 v[26:27], v[26:27], v[28:29]
	v_mul_f32_e32 v28, 0x3fb8aa3b, v10
	v_mul_f32_e32 v29, 0x3fb8aa3b, v11
	v_exp_f32_e32 v28, v28
	v_exp_f32_e32 v29, v29
	v_mul_f32_e32 v30, 0x3fb8aa3b, v30
	v_mul_f32_e32 v55, 0x3fb8aa3b, v55
	v_exp_f32_e32 v60, v30
	v_exp_f32_e32 v61, v55
	v_pk_add_f32 v[28:29], v[28:29], 1.0 op_sel_hi:[1,0] neg_lo:[1,0] neg_hi:[1,0]
	v_mul_f32_e32 v30, 0x3fb8aa3b, v12
	v_cvt_pk_bf16_f32 v26, v26, v27
	v_pk_mul_f32 v[28:29], v[28:29], v[60:61]
	v_exp_f32_e32 v60, v30
	v_mul_f32_e32 v30, 0x3fb8aa3b, v13
	v_exp_f32_e32 v61, v30
	v_sub_f32_e32 v30, v24, v31
	v_sub_f32_e32 v31, v24, v57
	v_mul_f32_e32 v30, 0x3fb8aa3b, v30
	v_mul_f32_e32 v31, 0x3fb8aa3b, v31
	v_exp_f32_e32 v30, v30
	v_exp_f32_e32 v31, v31
	v_pk_add_f32 v[56:57], v[60:61], 1.0 op_sel_hi:[1,0] neg_lo:[1,0] neg_hi:[1,0]
	v_cvt_pk_bf16_f32 v27, v28, v29
	v_sub_f32_e32 v29, v24, v59
	v_pk_mul_f32 v[30:31], v[56:57], v[30:31]
	v_sub_f32_e32 v25, v24, v25
	v_cvt_pk_bf16_f32 v28, v30, v31
	v_mul_f32_e32 v30, 0x3fb8aa3b, v14
	v_mul_f32_e32 v31, 0x3fb8aa3b, v15
	v_exp_f32_e32 v30, v30
	v_exp_f32_e32 v31, v31
	v_mul_f32_e32 v29, 0x3fb8aa3b, v29
	v_mul_f32_e32 v25, 0x3fb8aa3b, v25
	v_exp_f32_e32 v56, v29
	v_exp_f32_e32 v57, v25
	v_pk_add_f32 v[30:31], v[30:31], 1.0 op_sel_hi:[1,0] neg_lo:[1,0] neg_hi:[1,0]
	s_nop 0
	v_pk_mul_f32 v[30:31], v[30:31], v[56:57]
	s_nop 0
	v_cvt_pk_bf16_f32 v29, v30, v31
	ds_write_b128 v47, v[26:29] offset:16
	s_and_saveexec_b64 s[0:1], s[14:15]
	s_cbranch_execz .LBB0_162
	v_mul_f32_e32 v24, 0x3fb8aa3b, v24
	v_exp_f32_e32 v24, v24
	global_store_dword v[42:43], v24, off
